# A2b: next iteration score rows pre-touched into L2 while the bitwise search runs
# speedup vs baseline: 1.0066x; 1.0066x over previous
; __global__ void __launch_bounds__(512) mega_fwd(Params P) {
;     ...
;             const int NIT = 2 * 2 * SEQ * REP_A2;
;             for (int itA_ = gw; itA_ < NIT; itA_ += 2 * NGW) {
;                 const int itB_ = itA_ + NGW;
;                 const int itA = itA_ & (2 * 2 * SEQ - 1), itB = itB_ & (2 * 2 * SEQ - 1);
;                 const bool hasB = itB_ < NIT;
;                 unsigned a0 = 0u, a1 = 0u, c0 = 0u, c1 = 0u;
;                 TK_LOAD(itA, a0, a1);
;                 if (hasB) TK_LOAD(itB, c0, c1);
;                 const int curA = (itA & (SEQ - 1)) >> 6, curB = (itB & (SEQ - 1)) >> 6;
;                 unsigned TA = 0u, TB = 0u;
;                 bool dA = curA <= 15, dB = !hasB || curB <= 15;
;     ...
;                     const unsigned trA = TA | (1u << bit), trB = TB | (1u << bit);
;                     const int cA = __popcll(__ballot(a0 >= trA)) + __popcll(__ballot(a1 >= trA));
;                     const int cB = __popcll(__ballot(c0 >= trB)) + __popcll(__ballot(c1 >= trB));
;                     if (!dA) { if (cA == 13) { TA = trA - 1u; dA = true; } else if (cA > 13) TA = trA; }
;                     if (!dB) { if (cB == 13) { TB = trB - 1u; dB = true; } else if (cB > 13) TB = trB; }
;                 }
.LBB0_1198:
	s_waitcnt vmcnt(0) lgkmcnt(0)
	s_mov_b64 s[52:53], exec
	s_mov_b64 exec, s[44:45]
	v_add_f32_e32 v20, v7, v20
	v_add_u32_e32 v7, 1, v20
	s_mov_b64 exec, s[46:47]
	v_add_f32_e32 v21, v6, v21
	v_add_u32_e32 v6, 1, v21
	s_mov_b64 exec, s[48:49]
	v_add_f32_e32 v22, v5, v22
	v_add_u32_e32 v5, 1, v22
	s_mov_b64 exec, s[50:51]
	v_add_f32_e32 v23, v4, v23
	v_add_u32_e32 v4, 1, v23
	s_mov_b64 exec, s[52:53]
	s_add_i32 s54, s29, s22
	s_cmpk_gt_i32 s54, 0x7fff
	s_cbranch_scc1 .La2b_nopf
	v_lshlrev_b32_e32 v28, 2, v2
	v_mov_b32_e32 v29, v1
	s_and_b32 s55, s54, 0x7fff
	s_lshl_b32 s55, s55, 9
	s_add_u32 s56, s23, s55
	s_addc_u32 s57, s24, 0
	v_lshl_add_u64 v[30:31], s[56:57], 0, v[28:29]
	global_load_dword v32, v[30:31], off
	global_load_dword v33, v[30:31], off offset:256
	s_add_u32 s56, s25, s55
	s_addc_u32 s57, s26, 0
	v_lshl_add_u64 v[30:31], s[56:57], 0, v[28:29]
	global_load_dword v34, v[30:31], off
	global_load_dword v35, v[30:31], off offset:256
	s_add_i32 s54, s54, s22
	s_cmpk_gt_i32 s54, 0x7fff
	s_cbranch_scc1 .La2b_nopf
	s_and_b32 s55, s54, 0x7fff
	s_lshl_b32 s55, s55, 9
	s_add_u32 s56, s23, s55
	s_addc_u32 s57, s24, 0
	v_lshl_add_u64 v[30:31], s[56:57], 0, v[28:29]
	global_load_dword v36, v[30:31], off
	global_load_dword v37, v[30:31], off offset:256
	s_add_u32 s56, s25, s55
	s_addc_u32 s57, s26, 0
	v_lshl_add_u64 v[30:31], s[56:57], 0, v[28:29]
	global_load_dword v38, v[30:31], off
	global_load_dword v39, v[30:31], off offset:256
.La2b_nopf:
	s_cmp_lt_u32 s37, 16
	s_cselect_b64 s[20:21], -1, 0
	s_cmp_gt_u32 s37, 15
	s_cselect_b64 s[18:19], -1, 0
	s_and_b64 s[6:7], s[20:21], s[16:17]
	s_mov_b32 s39, 0
	s_and_b64 vcc, exec, s[6:7]
	s_mov_b32 s38, 0
	s_cbranch_vccnz .LBB0_1213
	s_mov_b32 s40, 30
	s_branch .LBB0_1202
